# v026 + P3: the first-half group merge (memory-bound, independent of the QKV GEMM) moved from the head of the phase to a class-dependent tile boundary inside the GEMM unit loop (class (bx>>3)&3 merges
# speedup vs baseline: 1.0030x; 1.0026x over previous
; #define PG8_STAGE(bufoff, gbase, voff) do { _Pragma("unroll") for (int _i = 0; _i < 2; ++_i) \
;         __builtin_amdgcn_global_load_lds((const unsigned*)((const char*)(gbase) + (voff)[_i]), (PG8_LAS unsigned*)(lds + (bufoff) + ldsw + _i * 8192), 16, 0, PG8_LOAD_AUX); } while (0)
; #define PG8_BAR __builtin_amdgcn_s_barrier()
; #define REP(k) for (int rep_ = 0; rep_ < ((((PROBE_REP) >> (k)) & 1) ? 2 : 1); ++rep_)
; template <class Epi, class Sched, bool ALIGN_EPI = false, bool SP2 = false>
; __device__ __forceinline__ void gemm_phase(PG8_LAS unsigned char* lds, const Gemm g, const Sched& S, const Epi& E) {
;     ...
;     const char* cA = (const char*)g.A + (size_t)cur.pm * tstepA + (size_t)cur.pn * apn; const char* cB = (const char*)g.Bt + (size_t)cur.pn * tstepB;
;     S.a_ready(cur);
;     if constexpr (SP2) {
;         PG8_STAGE(PG8_SB(0, 0), cB, voffB); PG8_STAGE(PG8_SB(0, 1), cB + hstepB, voffB); PG8_STAGE(PG8_SA(0, 0), cA, voffA); PG8_STAGE(PG8_SA(0, 1), cA + hstepA, voffA);
;         if (wr == 1) PG8_BAR;
; __global__ void __launch_bounds__(NTHREADS, 2) trunk_fwd(Args args) {
;     ...
;     if (IN(3)) { REP(3) merge_half(Og, L2, XN, gtid, gthreads);
;         stagger(bx); pg8::Gemm g{XN + (size_t)MH * D, Wqkv_t, MH, NQKV, D, D, 0}; pg8::StaticOrder S; S.init(MH, NQKV, G, bx); pg8::EpiBf16W E{QKV, NQKV, nullptr};
;         pg8::gemm_phase<pg8::EpiBf16W, pg8::StaticOrder, true, true>(lds, g, S, E); }
.LBB0_356:
	s_cmp_lt_i32 s84, 4
	s_cselect_b64 s[6:7], -1, 0
	s_and_b64 s[0:1], s[6:7], s[0:1]
	s_andn2_b64 vcc, exec, s[0:1]
	v_readlane_b32 s0, v239, 33
	s_nop 1
	v_add_u32_e32 v155, s0, v154
	s_mov_b32 s77, 1
	s_cbranch_vccnz .LBB0_376
	s_mov_b32 s77, 0
	s_memrealtime s[0:1]
	s_waitcnt lgkmcnt(0)
	s_memrealtime s[0:1]
	s_waitcnt lgkmcnt(0)
	v_readlane_b32 s0, v239, 0
	s_cmpk_lt_i32 s0, 0x900
	v_readfirstlane_b32 s3, v154
	s_cbranch_scc0 .LBB0_376
	v_lshlrev_b32_e32 v0, 4, v154
	v_lshrrev_b32_e32 v3, 5, v154
	v_lshrrev_b32_e32 v6, 1, v154
	v_add_u32_e32 v8, 0x2000, v0
	v_and_b32_e32 v3, 4, v3
	v_bfe_u32 v5, v154, 2, 2
	v_and_b32_e32 v6, 24, v6
	v_lshrrev_b32_e32 v2, 6, v8
	v_or3_b32 v3, v3, v5, v6
	s_movk_i32 s0, 0x1c0
	v_and_b32_e32 v5, 32, v154
	v_lshrrev_b32_e32 v1, 7, v8
	v_and_or_b32 v2, v2, s0, v3
	v_bitop3_b32 v9, v0, v5, 48 bitop3:0x6c
	v_and_b32_e32 v10, 64, v154
	v_bfe_u32 v11, v154, 2, 4
	s_movk_i32 s0, 0xf0
	s_add_u32 s33, s82, 0x5c00000
	v_lshrrev_b32_e32 v4, 2, v154
	v_or_b32_e32 v0, v9, v10
	v_and_or_b32 v1, v1, s0, v11
	s_movk_i32 s0, 0xc0
	v_readlane_b32 s2, v239, 0
	s_addc_u32 s36, s83, 0
	v_lshl_or_b32 v128, v2, 11, v0
	v_lshl_or_b32 v130, v1, 11, v0
	v_lshrrev_b32_e32 v1, 3, v154
	v_and_or_b32 v2, v4, s0, v3
	s_movk_i32 s0, 0x70
	s_ashr_i32 s42, s2, 31
	v_and_or_b32 v1, v1, s0, v11
	s_lshr_b32 s0, s42, 29
	s_add_i32 s0, s2, s0
	s_lshr_b32 s5, s3, 6
	s_ashr_i32 s1, s0, 3
	s_and_b32 s0, s0, -8
	s_lshr_b32 s4, s3, 8
	s_lshl_b32 s37, s5, 10
	s_sub_i32 s0, s2, s0
	s_cmp_lt_i32 s0, 0
	s_movk_i32 s43, 0x121
	s_cselect_b32 s2, s43, 0x120
	s_mul_i32 s0, s0, s2
	s_add_i32 s0, s0, s1
	s_mul_hi_i32 s1, s0, 0x38e38e39
	s_lshr_b32 s2, s1, 31
	s_ashr_i32 s1, s1, 5
	s_add_i32 s1, s1, s2
	s_lshl_b32 s8, s1, 2
	s_mulk_i32 s1, 0x90
	s_sub_i32 s0, s0, s1
	s_sext_i32_i16 s1, s0
	s_bfe_u32 s1, s1, 0x2001d
	s_add_i32 s1, s0, s1
	s_sext_i32_i16 s2, s1
	s_and_b32 s1, s1, 0xfffc
	s_sub_i32 s0, s0, s1
	s_sext_i32_i16 s0, s0
	s_lshr_b32 s2, s2, 2
	s_add_i32 s0, s8, s0
	s_ashr_i32 s1, s0, 31
	s_bfe_i64 s[10:11], s[2:3], 0x100000
	s_lshl_b64 s[8:9], s[0:1], 19
	s_lshl_b64 s[10:11], s[10:11], 19
	s_add_u32 s22, s64, s10
	s_addc_u32 s23, s65, s11
	s_add_i32 s44, s37, 0
	v_lshl_or_b32 v132, v2, 11, v0
	s_add_i32 m0, s44, 0x10000
	v_lshl_or_b32 v134, v1, 11, v0
	global_load_lds_dwordx4 v132, s[22:23]
	s_add_i32 m0, s44, 0x12000
	s_add_u32 s10, s22, 0x10000
	global_load_lds_dwordx4 v128, s[22:23]
	s_addc_u32 s11, s23, 0
	s_add_i32 m0, s44, 0x14000
	v_mov_b32_e32 v137, 0
	global_load_lds_dwordx4 v132, s[10:11]
	s_add_i32 m0, s44, 0x16000
	s_add_u32 s20, s33, s8
	s_addc_u32 s21, s36, s9
	s_add_i32 s45, s44, 0x2000
	global_load_lds_dwordx4 v128, s[10:11]
	s_mov_b32 m0, s44
	s_add_u32 s8, s20, 0x40000
	global_load_lds_dwordx4 v134, s[20:21]
	s_mov_b32 m0, s45
	s_addc_u32 s9, s21, 0
	s_add_i32 s46, s44, 0x4000
	global_load_lds_dwordx4 v130, s[20:21]
	s_mov_b32 m0, s46
	s_add_i32 s47, s44, 0x6000
	global_load_lds_dwordx4 v134, s[8:9]
	s_mov_b32 m0, s47
	v_mov_b32_e32 v133, v137
	global_load_lds_dwordx4 v130, s[8:9]
	v_mov_b32_e32 v129, v137
	v_mov_b32_e32 v135, v137
	v_mov_b32_e32 v131, v137
	s_cmp_eq_u32 s4, 1
	s_mov_b32 s48, 0
	v_lshl_add_u64 v[6:7], s[22:23], 0, v[132:133]
	v_lshl_add_u64 v[4:5], s[22:23], 0, v[128:129]
	v_lshl_add_u64 v[0:1], s[20:21], 0, v[134:135]
	s_cselect_b64 s[8:9], -1, 0
	s_cmp_lg_u32 s4, 1
	v_lshl_add_u64 v[2:3], s[20:21], 0, v[130:131]
	s_cbranch_scc1 .LBB0_363
	s_barrier

; __device__ __forceinline__ unsigned cvt_pk_bf16(float lo, float hi) { const cvt_f32x2_t v = {lo, hi}; const cvt_bf16x2_t b = __builtin_convertvector(v, cvt_bf16x2_t); return __builtin_bit_cast(unsigned, b); }
; __device__ __forceinline__ unsigned swap8(unsigned v) { return (unsigned)__builtin_amdgcn_update_dpp(0, (int)v, 0x128  , 0xF, 0xF, false); }
; __device__ __forceinline__ void wide_store(bf16_t* O, int ldc, int rowg  , int col0  , int fr, u32x4 w0, u32x4 w1) {
;     const bool lo = fr < 8;
;     u32x4 snd = lo ? w1 : w0, rcv;
;     rcv.x = swap8(snd.x); rcv.y = swap8(snd.y); rcv.z = swap8(snd.z); rcv.w = swap8(snd.w);
;     const u32x4 first = lo ? w0 : rcv, second = lo ? rcv : w1;
;     bf16_t* p = O + (size_t)(rowg + (fr & 7)) * ldc + col0 + (lo ? 0 : 32);
;     __builtin_nontemporal_store(first, (u32x4*)p); __builtin_nontemporal_store(second, (u32x4*)(p + (size_t)8 * ldc));
; }
;     __device__ __forceinline__ void operator()(const f32x4 (&acc)[2][2][4][2], const Unit& u, int wr, int wc, int fr, int fq) const {
;         const int col0 = u.pn * BM + wc * 64 + 8 * fq;
; #pragma unroll
;         for (int ai = 0; ai < 2; ++ai)
; #pragma unroll
;             for (int m = 0; m < 4; ++m) { const int rowg = u.pm * BM + ai * HALF + wr * 64 + m * 16;
;                 const float sc = slots ? rstd_from_slots(slots, rowg + fr, fq) : 1.0f;
;                 u32x4 w[2];
; #pragma unroll
;                 for (int bj = 0; bj < 2; ++bj) { const f32x4 v0 = acc[ai][bj][m][0] * sc, v1 = acc[ai][bj][m][1] * sc;
;                     w[bj].x = cvt_pk_bf16(v0[0], v0[1]); w[bj].y = cvt_pk_bf16(v0[2], v0[3]); w[bj].z = cvt_pk_bf16(v1[0], v1[1]); w[bj].w = cvt_pk_bf16(v1[2], v1[3]); }
;                 wide_store(O, ldc, rowg, col0, fr, w[0], w[1]); }
.LBB0_372:
	v_readlane_b32 s30, v239, 49
	v_readlane_b32 s31, v239, 50
	s_lshl_b32 s0, s0, 8
	v_lshl_or_b32 v162, s1, 8, v147
	v_add_u32_e32 v164, s0, v148
	v_ashrrev_i32_e32 v163, 31, v162
	s_mov_b32 s98, 0x24000
	s_mov_b32 s99, 0
	v_lshlrev_b64 v[162:163], 1, v[162:163]
	v_mov_b64_e32 v[168:169], s[30:31]
	v_mad_i64_i32 v[164:165], s[20:21], v164, s55, v[168:169]
	v_lshl_add_u64 v[162:163], v[162:163], 0, v[136:137]
	v_lshl_add_u64 v[164:165], v[164:165], 0, v[162:163]
	v_cvt_pk_bf16_f32 v124, v124, v125
	v_cvt_pk_bf16_f32 v125, v126, v127
	v_cvt_pk_bf16_f32 v126, v120, v121
	v_cvt_pk_bf16_f32 v127, v122, v123
	v_cvt_pk_bf16_f32 v116, v116, v117
	v_cvt_pk_bf16_f32 v117, v118, v119
	v_cvt_pk_bf16_f32 v118, v112, v113
	v_cvt_pk_bf16_f32 v119, v114, v115
	v_cvt_pk_bf16_f32 v108, v108, v109
	v_cvt_pk_bf16_f32 v109, v110, v111
	v_cvt_pk_bf16_f32 v110, v104, v105
	v_cvt_pk_bf16_f32 v111, v106, v107
	v_cvt_pk_bf16_f32 v100, v100, v101
	v_cvt_pk_bf16_f32 v101, v102, v103
	v_cvt_pk_bf16_f32 v102, v96, v97
	v_cvt_pk_bf16_f32 v103, v98, v99
	s_not_b64 vcc, s[2:3]
	v_cndmask_b32_dpp v112, v124, v116, vcc row_ror:8 row_mask:0xf bank_mask:0xf
	v_cndmask_b32_dpp v113, v125, v117, vcc row_ror:8 row_mask:0xf bank_mask:0xf
	v_cndmask_b32_dpp v114, v126, v118, vcc row_ror:8 row_mask:0xf bank_mask:0xf
	v_cndmask_b32_dpp v115, v127, v119, vcc row_ror:8 row_mask:0xf bank_mask:0xf
	v_cndmask_b32_dpp v96, v108, v100, vcc row_ror:8 row_mask:0xf bank_mask:0xf
	v_cndmask_b32_dpp v97, v109, v101, vcc row_ror:8 row_mask:0xf bank_mask:0xf
	v_cndmask_b32_dpp v98, v110, v102, vcc row_ror:8 row_mask:0xf bank_mask:0xf
	v_cndmask_b32_dpp v99, v111, v103, vcc row_ror:8 row_mask:0xf bank_mask:0xf
	s_mov_b64 vcc, s[2:3]
	v_cndmask_b32_dpp v120, v116, v124, vcc row_ror:8 row_mask:0xf bank_mask:0xf
	v_cndmask_b32_dpp v121, v117, v125, vcc row_ror:8 row_mask:0xf bank_mask:0xf
	v_cndmask_b32_dpp v122, v118, v126, vcc row_ror:8 row_mask:0xf bank_mask:0xf
	v_cndmask_b32_dpp v123, v119, v127, vcc row_ror:8 row_mask:0xf bank_mask:0xf
	v_cndmask_b32_dpp v104, v100, v108, vcc row_ror:8 row_mask:0xf bank_mask:0xf
	v_cndmask_b32_dpp v105, v101, v109, vcc row_ror:8 row_mask:0xf bank_mask:0xf
	v_cndmask_b32_dpp v106, v102, v110, vcc row_ror:8 row_mask:0xf bank_mask:0xf
	v_cndmask_b32_dpp v107, v103, v111, vcc row_ror:8 row_mask:0xf bank_mask:0xf
	global_store_dwordx4 v[164:165], v[120:123], off nt
	v_lshl_add_u64 v[166:167], v[164:165], 0, s[98:99]
	global_store_dwordx4 v[166:167], v[112:115], off nt
	v_lshl_add_u64 v[164:165], v[166:167], 0, s[98:99]
	global_store_dwordx4 v[164:165], v[104:107], off nt
	v_lshl_add_u64 v[166:167], v[164:165], 0, s[98:99]
	global_store_dwordx4 v[166:167], v[96:99], off nt
	v_cvt_pk_bf16_f32 v92, v92, v93
	v_cvt_pk_bf16_f32 v93, v94, v95
	v_cvt_pk_bf16_f32 v94, v88, v89
	v_cvt_pk_bf16_f32 v95, v90, v91
	v_cvt_pk_bf16_f32 v84, v84, v85
	v_cvt_pk_bf16_f32 v85, v86, v87
	v_cvt_pk_bf16_f32 v86, v80, v81
	v_cvt_pk_bf16_f32 v87, v82, v83
	v_cvt_pk_bf16_f32 v76, v76, v77
	v_cvt_pk_bf16_f32 v77, v78, v79
	v_cvt_pk_bf16_f32 v78, v72, v73
	v_cvt_pk_bf16_f32 v79, v74, v75
	v_cvt_pk_bf16_f32 v68, v68, v69
	v_cvt_pk_bf16_f32 v69, v70, v71
	v_cvt_pk_bf16_f32 v70, v64, v65
	v_cvt_pk_bf16_f32 v71, v66, v67
	s_not_b64 vcc, s[2:3]
	v_cndmask_b32_dpp v80, v92, v84, vcc row_ror:8 row_mask:0xf bank_mask:0xf
	v_cndmask_b32_dpp v81, v93, v85, vcc row_ror:8 row_mask:0xf bank_mask:0xf
	v_cndmask_b32_dpp v82, v94, v86, vcc row_ror:8 row_mask:0xf bank_mask:0xf
	v_cndmask_b32_dpp v83, v95, v87, vcc row_ror:8 row_mask:0xf bank_mask:0xf
	v_cndmask_b32_dpp v64, v76, v68, vcc row_ror:8 row_mask:0xf bank_mask:0xf
	v_cndmask_b32_dpp v65, v77, v69, vcc row_ror:8 row_mask:0xf bank_mask:0xf
	v_cndmask_b32_dpp v66, v78, v70, vcc row_ror:8 row_mask:0xf bank_mask:0xf
	v_cndmask_b32_dpp v67, v79, v71, vcc row_ror:8 row_mask:0xf bank_mask:0xf
	s_mov_b64 vcc, s[2:3]
	v_cndmask_b32_dpp v88, v84, v92, vcc row_ror:8 row_mask:0xf bank_mask:0xf
	v_cndmask_b32_dpp v89, v85, v93, vcc row_ror:8 row_mask:0xf bank_mask:0xf
	v_cndmask_b32_dpp v90, v86, v94, vcc row_ror:8 row_mask:0xf bank_mask:0xf
	v_cndmask_b32_dpp v91, v87, v95, vcc row_ror:8 row_mask:0xf bank_mask:0xf
	v_cndmask_b32_dpp v72, v68, v76, vcc row_ror:8 row_mask:0xf bank_mask:0xf
	v_cndmask_b32_dpp v73, v69, v77, vcc row_ror:8 row_mask:0xf bank_mask:0xf
	v_cndmask_b32_dpp v74, v70, v78, vcc row_ror:8 row_mask:0xf bank_mask:0xf
	v_cndmask_b32_dpp v75, v71, v79, vcc row_ror:8 row_mask:0xf bank_mask:0xf
	v_lshl_add_u64 v[164:165], v[166:167], 0, s[98:99]
	global_store_dwordx4 v[164:165], v[88:91], off nt
	v_lshl_add_u64 v[166:167], v[164:165], 0, s[98:99]
	global_store_dwordx4 v[166:167], v[80:83], off nt
	v_lshl_add_u64 v[164:165], v[166:167], 0, s[98:99]
	global_store_dwordx4 v[164:165], v[72:75], off nt
; __device__ __forceinline__ unsigned cvt_pk_bf16(float lo, float hi) { const cvt_f32x2_t v = {lo, hi}; const cvt_bf16x2_t b = __builtin_convertvector(v, cvt_bf16x2_t); return __builtin_bit_cast(unsigned, b); }
;     __device__ __forceinline__ void operator()(const f32x4 (&acc)[2][2][4][2], const Unit& u, int wr, int wc, int fr, int fq) const {
;     ...
;             for (int m = 0; m < 4; ++m) { const int rowg = u.pm * BM + ai * HALF + wr * 64 + m * 16;
;                 const float sc = slots ? rstd_from_slots(slots, rowg + fr, fq) : 1.0f;
;                 u32x4 w[2];
; #pragma unroll
;                 for (int bj = 0; bj < 2; ++bj) { const f32x4 v0 = acc[ai][bj][m][0] * sc, v1 = acc[ai][bj][m][1] * sc;
;                     w[bj].x = cvt_pk_bf16(v0[0], v0[1]); w[bj].y = cvt_pk_bf16(v0[2], v0[3]); w[bj].z = cvt_pk_bf16(v1[0], v1[1]); w[bj].w = cvt_pk_bf16(v1[2], v1[3]); }
;                 wide_store(O, ldc, rowg, col0, fr, w[0], w[1]); }
; __device__ __forceinline__ void merge_half(const bf16* __restrict__ Og, const float* __restrict__ L2, bf16* __restrict__ O  , int gtid, int gthreads) {
;     for (int idx = gtid; idx < MH * 128; idx += gthreads) {
;         const int tl = idx >> 7, ch = idx & 127, h = ch >> 4;
	v_lshl_add_u64 v[166:167], v[164:165], 0, s[98:99]
	global_store_dwordx4 v[166:167], v[64:67], off nt
	v_cvt_pk_bf16_f32 v60, v60, v61
	v_cvt_pk_bf16_f32 v61, v62, v63
	v_cvt_pk_bf16_f32 v62, v56, v57
	v_cvt_pk_bf16_f32 v63, v58, v59
	v_cvt_pk_bf16_f32 v52, v52, v53
	v_cvt_pk_bf16_f32 v53, v54, v55
	v_cvt_pk_bf16_f32 v54, v48, v49
	v_cvt_pk_bf16_f32 v55, v50, v51
	v_cvt_pk_bf16_f32 v44, v44, v45
	v_cvt_pk_bf16_f32 v45, v46, v47
	v_cvt_pk_bf16_f32 v46, v40, v41
	v_cvt_pk_bf16_f32 v47, v42, v43
	v_cvt_pk_bf16_f32 v36, v36, v37
	v_cvt_pk_bf16_f32 v37, v38, v39
	v_cvt_pk_bf16_f32 v38, v32, v33
	v_cvt_pk_bf16_f32 v39, v34, v35
	s_not_b64 vcc, s[2:3]
	v_cndmask_b32_dpp v48, v60, v52, vcc row_ror:8 row_mask:0xf bank_mask:0xf
	v_cndmask_b32_dpp v49, v61, v53, vcc row_ror:8 row_mask:0xf bank_mask:0xf
	v_cndmask_b32_dpp v50, v62, v54, vcc row_ror:8 row_mask:0xf bank_mask:0xf
	v_cndmask_b32_dpp v51, v63, v55, vcc row_ror:8 row_mask:0xf bank_mask:0xf
	v_cndmask_b32_dpp v32, v44, v36, vcc row_ror:8 row_mask:0xf bank_mask:0xf
	v_cndmask_b32_dpp v33, v45, v37, vcc row_ror:8 row_mask:0xf bank_mask:0xf
	v_cndmask_b32_dpp v34, v46, v38, vcc row_ror:8 row_mask:0xf bank_mask:0xf
	v_cndmask_b32_dpp v35, v47, v39, vcc row_ror:8 row_mask:0xf bank_mask:0xf
	s_mov_b64 vcc, s[2:3]
	v_cndmask_b32_dpp v56, v52, v60, vcc row_ror:8 row_mask:0xf bank_mask:0xf
	v_cndmask_b32_dpp v57, v53, v61, vcc row_ror:8 row_mask:0xf bank_mask:0xf
	v_cndmask_b32_dpp v58, v54, v62, vcc row_ror:8 row_mask:0xf bank_mask:0xf
	v_cndmask_b32_dpp v59, v55, v63, vcc row_ror:8 row_mask:0xf bank_mask:0xf
	v_cndmask_b32_dpp v40, v36, v44, vcc row_ror:8 row_mask:0xf bank_mask:0xf
	v_cndmask_b32_dpp v41, v37, v45, vcc row_ror:8 row_mask:0xf bank_mask:0xf
	v_cndmask_b32_dpp v42, v38, v46, vcc row_ror:8 row_mask:0xf bank_mask:0xf
	v_cndmask_b32_dpp v43, v39, v47, vcc row_ror:8 row_mask:0xf bank_mask:0xf
	s_mov_b32 s98, 0x144000
	v_lshl_add_u64 v[164:165], v[166:167], 0, s[98:99]
	s_mov_b32 s98, 0x24000
	global_store_dwordx4 v[164:165], v[56:59], off nt
	v_lshl_add_u64 v[166:167], v[164:165], 0, s[98:99]
	global_store_dwordx4 v[166:167], v[48:51], off nt
	v_lshl_add_u64 v[164:165], v[166:167], 0, s[98:99]
	global_store_dwordx4 v[164:165], v[40:43], off nt
	v_lshl_add_u64 v[166:167], v[164:165], 0, s[98:99]
	global_store_dwordx4 v[166:167], v[32:35], off nt
	v_cvt_pk_bf16_f32 v28, v28, v29
	v_cvt_pk_bf16_f32 v29, v30, v31
	v_cvt_pk_bf16_f32 v30, v24, v25
	v_cvt_pk_bf16_f32 v31, v26, v27
	v_cvt_pk_bf16_f32 v20, v20, v21
	v_cvt_pk_bf16_f32 v21, v22, v23
	v_cvt_pk_bf16_f32 v22, v16, v17
	v_cvt_pk_bf16_f32 v23, v18, v19
	v_cvt_pk_bf16_f32 v12, v12, v13
	v_cvt_pk_bf16_f32 v13, v14, v15
	v_cvt_pk_bf16_f32 v14, v8, v9
	v_cvt_pk_bf16_f32 v15, v10, v11
	v_cvt_pk_bf16_f32 v4, v4, v5
	v_cvt_pk_bf16_f32 v5, v6, v7
	v_cvt_pk_bf16_f32 v6, v0, v1
	v_cvt_pk_bf16_f32 v7, v2, v3
	s_not_b64 vcc, s[2:3]
	v_cndmask_b32_dpp v16, v28, v20, vcc row_ror:8 row_mask:0xf bank_mask:0xf
	v_cndmask_b32_dpp v17, v29, v21, vcc row_ror:8 row_mask:0xf bank_mask:0xf
	v_cndmask_b32_dpp v18, v30, v22, vcc row_ror:8 row_mask:0xf bank_mask:0xf
	v_cndmask_b32_dpp v19, v31, v23, vcc row_ror:8 row_mask:0xf bank_mask:0xf
	v_cndmask_b32_dpp v0, v12, v4, vcc row_ror:8 row_mask:0xf bank_mask:0xf
	v_cndmask_b32_dpp v1, v13, v5, vcc row_ror:8 row_mask:0xf bank_mask:0xf
	v_cndmask_b32_dpp v2, v14, v6, vcc row_ror:8 row_mask:0xf bank_mask:0xf
	v_cndmask_b32_dpp v3, v15, v7, vcc row_ror:8 row_mask:0xf bank_mask:0xf
	s_mov_b64 vcc, s[2:3]
	v_cndmask_b32_dpp v24, v20, v28, vcc row_ror:8 row_mask:0xf bank_mask:0xf
	v_cndmask_b32_dpp v25, v21, v29, vcc row_ror:8 row_mask:0xf bank_mask:0xf
	v_cndmask_b32_dpp v26, v22, v30, vcc row_ror:8 row_mask:0xf bank_mask:0xf
	v_cndmask_b32_dpp v27, v23, v31, vcc row_ror:8 row_mask:0xf bank_mask:0xf
	v_cndmask_b32_dpp v8, v4, v12, vcc row_ror:8 row_mask:0xf bank_mask:0xf
	v_cndmask_b32_dpp v9, v5, v13, vcc row_ror:8 row_mask:0xf bank_mask:0xf
	v_cndmask_b32_dpp v10, v6, v14, vcc row_ror:8 row_mask:0xf bank_mask:0xf
	v_cndmask_b32_dpp v11, v7, v15, vcc row_ror:8 row_mask:0xf bank_mask:0xf
	v_lshl_add_u64 v[164:165], v[166:167], 0, s[98:99]
	global_store_dwordx4 v[164:165], v[24:27], off nt
	v_lshl_add_u64 v[166:167], v[164:165], 0, s[98:99]
	global_store_dwordx4 v[166:167], v[16:19], off nt
	v_lshl_add_u64 v[164:165], v[166:167], 0, s[98:99]
	global_store_dwordx4 v[164:165], v[8:11], off nt
	v_lshl_add_u64 v[166:167], v[164:165], 0, s[98:99]
	global_store_dwordx4 v[166:167], v[0:3], off nt
	v_readlane_b32 s76, v239, 0
	s_bfe_u32 s76, s76, 0x20003
	s_lshl_b32 s76, s76, 1
	s_add_i32 s76, s76, 1
	s_cmp_lg_u32 s76, s48
	s_cbranch_scc1 .Lmrg_skip_P3
	s_mov_b32 s66, 0x200000
	v_cmp_gt_i32_e32 vcc, s66, v155
	s_and_saveexec_b64 s[66:67], vcc
	v_readlane_b32 s75, v239, 46
	s_cbranch_execz .Lmrg_done_P3a

; __device__ __forceinline__ unsigned cvtpk(float lo, float hi) { return pg8::cvt_pk_bf16(lo, hi); }
; __device__ __forceinline__ float bflo(unsigned u) { return __uint_as_float(u << 16); }
; __device__ __forceinline__ float bfhi(unsigned u) { return __uint_as_float(u & 0xffff0000u); }
; __device__ __forceinline__ void merge_half(const bf16* __restrict__ Og, const float* __restrict__ L2, bf16* __restrict__ O  , int gtid, int gthreads) {
;     for (int idx = gtid; idx < MH * 128; idx += gthreads) {
;         const int tl = idx >> 7, ch = idx & 127, h = ch >> 4;
;         const float l0 = L2[((size_t)0 * MH + tl) * 8 + h], l1 = L2[((size_t)1 * MH + tl) * 8 + h], l2 = L2[((size_t)2 * MH + tl) * 8 + h];
;         const float mx = fmaxf(l0, fmaxf(l1, l2));
;         float w0 = __builtin_amdgcn_exp2f(l0 - mx), w1 = __builtin_amdgcn_exp2f(l1 - mx), w2 = __builtin_amdgcn_exp2f(l2 - mx);
;         const float inv = __builtin_amdgcn_rcpf(w0 + w1 + w2); w0 *= inv; w1 *= inv; w2 *= inv;
;         const v4u a = __builtin_nontemporal_load((const v4u*)(Og + ((size_t)0 * MH + tl) * 1024 + ch * 8)), b = __builtin_nontemporal_load((const v4u*)(Og + ((size_t)1 * MH + tl) * 1024 + ch * 8)), c = __builtin_nontemporal_load((const v4u*)(Og + ((size_t)2 * MH + tl) * 1024 + ch * 8));
;         v4u o;
; #pragma unroll
;         for (int j = 0; j < 4; ++j) o[j] = cvtpk(w0 * bflo(a[j]) + w1 * bflo(b[j]) + w2 * bflo(c[j]), w0 * bfhi(a[j]) + w1 * bfhi(b[j]) + w2 * bfhi(c[j]));
;         __builtin_nontemporal_store(o, (v4u*)(O + (size_t)tl * 1024 + ch * 8));
;     }
	v_lshrrev_b32_e32 v0, 2, v154
	v_readlane_b32 s68, v239, 51
	v_and_b32_e32 v4, 28, v0
	v_mov_b32_e32 v5, 0
	v_readlane_b32 s69, v239, 52
	v_and_b32_e32 v2, 0x7f, v154
	s_mov_b64 s[70:71], 0x4000
	v_lshl_add_u64 v[0:1], s[68:69], 0, v[4:5]
	v_readlane_b32 s68, v239, 47
	v_lshlrev_b32_e32 v4, 4, v2
	v_readlane_b32 s69, v239, 48
	v_lshl_add_u64 v[2:3], s[80:81], 0, v[4:5]
	s_mov_b64 s[72:73], 0x8000
	v_lshl_add_u64 v[4:5], s[68:69], 0, v[4:5]
	s_mov_b64 s[68:69], 0
	s_mov_b32 s74, 0x1fffff
	v_mov_b32_e32 v6, v155
.Lmrg_loop_P3a:
	v_ashrrev_i32_e32 v8, 7, v6
	v_ashrrev_i32_e32 v9, 31, v8
	v_lshl_add_u64 v[12:13], v[8:9], 0, s[70:71]
	v_lshlrev_b64 v[10:11], 5, v[8:9]
	v_lshl_add_u64 v[14:15], v[8:9], 0, s[72:73]
	v_lshlrev_b64 v[20:21], 11, v[8:9]
	v_lshlrev_b64 v[18:19], 5, v[12:13]
	v_lshlrev_b64 v[12:13], 11, v[12:13]
	v_lshl_add_u64 v[16:17], v[0:1], 0, v[10:11]
	v_lshlrev_b64 v[22:23], 5, v[14:15]
	v_lshl_add_u64 v[8:9], v[2:3], 0, v[20:21]
	v_lshlrev_b64 v[14:15], 11, v[14:15]
	v_lshl_add_u64 v[18:19], v[0:1], 0, v[18:19]
	v_lshl_add_u64 v[12:13], v[2:3], 0, v[12:13]
	global_load_dwordx4 v[8:11], v[8:9], off nt
	v_lshl_add_u64 v[22:23], v[0:1], 0, v[22:23]
	v_lshl_add_u64 v[24:25], v[2:3], 0, v[14:15]
	global_load_dword v7, v[16:17], off
	global_load_dword v36, v[18:19], off
	global_load_dword v37, v[22:23], off
	s_nop 0
	global_load_dwordx4 v[12:15], v[12:13], off nt
	s_nop 0
	global_load_dwordx4 v[16:19], v[24:25], off nt
	v_add_u32_e32 v6, s75, v6
	v_cmp_lt_i32_e32 vcc, s74, v6
	s_or_b64 s[68:69], vcc, s[68:69]
	v_lshl_add_u64 v[20:21], v[4:5], 0, v[20:21]
	s_waitcnt vmcnt(0)
	v_and_b32_e32 v25, 0xffff0000, v9
	v_max3_f32 v38, v7, v36, v37
	v_lshlrev_b32_e32 v26, 16, v9
	v_lshlrev_b32_e32 v22, 16, v12
	v_and_b32_e32 v9, 0xffff0000, v12
	v_lshlrev_b32_e32 v34, 16, v16
	v_and_b32_e32 v35, 0xffff0000, v16
	v_lshlrev_b32_e32 v24, 16, v13
	v_and_b32_e32 v27, 0xffff0000, v13
	v_lshlrev_b32_e32 v12, 16, v17
	v_and_b32_e32 v13, 0xffff0000, v17
	v_lshlrev_b32_e32 v16, 16, v18
	v_and_b32_e32 v17, 0xffff0000, v18
	v_sub_f32_e32 v7, v7, v38
	v_sub_f32_e32 v18, v36, v38
	v_and_b32_e32 v31, 0xffff0000, v11
	v_lshlrev_b32_e32 v32, 16, v11
	v_lshlrev_b32_e32 v28, 16, v14
	v_and_b32_e32 v11, 0xffff0000, v14
	v_lshlrev_b32_e32 v30, 16, v15
	v_and_b32_e32 v33, 0xffff0000, v15
	v_lshlrev_b32_e32 v14, 16, v19
	v_and_b32_e32 v15, 0xffff0000, v19
	v_sub_f32_e32 v36, v37, v38
	v_exp_f32_e32 v19, v7
	v_exp_f32_e32 v18, v18
	v_exp_f32_e32 v7, v36
	v_and_b32_e32 v23, 0xffff0000, v8
	v_lshlrev_b32_e32 v8, 16, v8
	v_add_f32_e32 v36, v19, v18
	v_add_f32_e32 v36, v7, v36
	v_rcp_f32_e32 v36, v36
	v_and_b32_e32 v29, 0xffff0000, v10
	v_lshlrev_b32_e32 v10, 16, v10
	v_pk_mul_f32 v[18:19], v[18:19], v[36:37] op_sel_hi:[1,0]
	s_nop 0
	v_pk_mul_f32 v[8:9], v[18:19], v[8:9] op_sel:[1,0] op_sel_hi:[0,1]
	v_pk_mul_f32 v[26:27], v[18:19], v[26:27] op_sel:[1,0] op_sel_hi:[0,1]
	v_pk_mul_f32 v[10:11], v[18:19], v[10:11] op_sel:[1,0] op_sel_hi:[0,1]
	v_pk_mul_f32 v[32:33], v[18:19], v[32:33] op_sel:[1,0] op_sel_hi:[0,1]
	v_mul_f32_e32 v38, v7, v36
	v_pk_fma_f32 v[8:9], v[18:19], v[22:23], v[8:9]
	v_pk_fma_f32 v[22:23], v[18:19], v[24:25], v[26:27]
	v_pk_fma_f32 v[10:11], v[18:19], v[28:29], v[10:11]
	v_pk_fma_f32 v[18:19], v[18:19], v[30:31], v[32:33]
	v_pk_fma_f32 v[8:9], v[38:39], v[34:35], v[8:9] op_sel_hi:[0,1,1]
	v_pk_fma_f32 v[12:13], v[38:39], v[12:13], v[22:23] op_sel_hi:[0,1,1]
	v_pk_fma_f32 v[10:11], v[38:39], v[16:17], v[10:11] op_sel_hi:[0,1,1]
	v_pk_fma_f32 v[14:15], v[38:39], v[14:15], v[18:19] op_sel_hi:[0,1,1]
	v_cvt_pk_bf16_f32 v8, v8, v9
	v_cvt_pk_bf16_f32 v9, v12, v13
	v_cvt_pk_bf16_f32 v10, v10, v11
	v_cvt_pk_bf16_f32 v11, v14, v15
	global_store_dwordx4 v[20:21], v[8:11], off nt
	s_andn2_b64 exec, exec, s[68:69]
	s_cbranch_execnz .Lmrg_loop_P3a
.Lmrg_done_P3a:
	s_or_b64 exec, exec, s[66:67]
	s_mov_b32 s77, 1
.Lmrg_skip_P3:
	s_andn2_b64 vcc, exec, s[4:5]
	s_mov_b64 s[0:1], -1
	s_cbranch_vccnz .LBB0_365
	s_andn2_b64 vcc, exec, s[8:9]
	s_cbranch_vccnz .LBB0_364
	s_barrier
	s_branch .LBB0_364

; __device__ __forceinline__ void merge_half(const bf16* __restrict__ Og, const float* __restrict__ L2, bf16* __restrict__ O  , int gtid, int gthreads) {
;     for (int idx = gtid; idx < MH * 128; idx += gthreads) {
;         const int tl = idx >> 7, ch = idx & 127, h = ch >> 4;
.LBB0_376:
	s_cmp_eq_u32 s77, 1
	s_cbranch_scc1 .Lmrg_none_P3
	s_mov_b32 s66, 0x200000
	v_cmp_gt_i32_e32 vcc, s66, v155
	s_and_saveexec_b64 s[66:67], vcc
	v_readlane_b32 s75, v239, 46
	s_cbranch_execz .Lmrg_done_P3b

; __device__ __forceinline__ void merge_half(const bf16* __restrict__ Og, const float* __restrict__ L2, bf16* __restrict__ O  , int gtid, int gthreads) {
;     for (int idx = gtid; idx < MH * 128; idx += gthreads) {
;         const int tl = idx >> 7, ch = idx & 127, h = ch >> 4;
;         const float l0 = L2[((size_t)0 * MH + tl) * 8 + h], l1 = L2[((size_t)1 * MH + tl) * 8 + h], l2 = L2[((size_t)2 * MH + tl) * 8 + h];
;         const float mx = fmaxf(l0, fmaxf(l1, l2));
;         float w0 = __builtin_amdgcn_exp2f(l0 - mx), w1 = __builtin_amdgcn_exp2f(l1 - mx), w2 = __builtin_amdgcn_exp2f(l2 - mx);
;         const float inv = __builtin_amdgcn_rcpf(w0 + w1 + w2); w0 *= inv; w1 *= inv; w2 *= inv;
;         const v4u a = __builtin_nontemporal_load((const v4u*)(Og + ((size_t)0 * MH + tl) * 1024 + ch * 8)), b = __builtin_nontemporal_load((const v4u*)(Og + ((size_t)1 * MH + tl) * 1024 + ch * 8)), c = __builtin_nontemporal_load((const v4u*)(Og + ((size_t)2 * MH + tl) * 1024 + ch * 8));
	v_lshrrev_b32_e32 v0, 2, v154
	v_readlane_b32 s68, v239, 51
	v_and_b32_e32 v4, 28, v0
	v_mov_b32_e32 v5, 0
	v_readlane_b32 s69, v239, 52
	v_and_b32_e32 v2, 0x7f, v154
	s_mov_b64 s[70:71], 0x4000
	v_lshl_add_u64 v[0:1], s[68:69], 0, v[4:5]
	v_readlane_b32 s68, v239, 47
	v_lshlrev_b32_e32 v4, 4, v2
	v_readlane_b32 s69, v239, 48
	v_lshl_add_u64 v[2:3], s[80:81], 0, v[4:5]
	s_mov_b64 s[72:73], 0x8000
	v_lshl_add_u64 v[4:5], s[68:69], 0, v[4:5]
	s_mov_b64 s[68:69], 0
	s_mov_b32 s74, 0x1fffff
	v_mov_b32_e32 v6, v155

; __device__ __forceinline__ unsigned cvtpk(float lo, float hi) { return pg8::cvt_pk_bf16(lo, hi); }
; __device__ __forceinline__ float bflo(unsigned u) { return __uint_as_float(u << 16); }
; __device__ __forceinline__ float bfhi(unsigned u) { return __uint_as_float(u & 0xffff0000u); }
; __device__ __forceinline__ void merge_half(const bf16* __restrict__ Og, const float* __restrict__ L2, bf16* __restrict__ O  , int gtid, int gthreads) {
;     for (int idx = gtid; idx < MH * 128; idx += gthreads) {
;         const int tl = idx >> 7, ch = idx & 127, h = ch >> 4;
;         const float l0 = L2[((size_t)0 * MH + tl) * 8 + h], l1 = L2[((size_t)1 * MH + tl) * 8 + h], l2 = L2[((size_t)2 * MH + tl) * 8 + h];
;         const float mx = fmaxf(l0, fmaxf(l1, l2));
;         float w0 = __builtin_amdgcn_exp2f(l0 - mx), w1 = __builtin_amdgcn_exp2f(l1 - mx), w2 = __builtin_amdgcn_exp2f(l2 - mx);
;         const float inv = __builtin_amdgcn_rcpf(w0 + w1 + w2); w0 *= inv; w1 *= inv; w2 *= inv;
;         const v4u a = __builtin_nontemporal_load((const v4u*)(Og + ((size_t)0 * MH + tl) * 1024 + ch * 8)), b = __builtin_nontemporal_load((const v4u*)(Og + ((size_t)1 * MH + tl) * 1024 + ch * 8)), c = __builtin_nontemporal_load((const v4u*)(Og + ((size_t)2 * MH + tl) * 1024 + ch * 8));
;         v4u o;
; #pragma unroll
;         for (int j = 0; j < 4; ++j) o[j] = cvtpk(w0 * bflo(a[j]) + w1 * bflo(b[j]) + w2 * bflo(c[j]), w0 * bfhi(a[j]) + w1 * bfhi(b[j]) + w2 * bfhi(c[j]));
;         __builtin_nontemporal_store(o, (v4u*)(O + (size_t)tl * 1024 + ch * 8));
;     }
.Lmrg_done_P3b:
	s_or_b64 exec, exec, s[66:67]
